# attention V^T image: keys 4..7 / 8..11 of each 16-key group swapped so an MFMA B-operand lane's eight keys are 16 contiguous bytes: 32 ds_read2_b64 (2-way bank conflict) become conflict-free ds_read_b
# speedup vs baseline: 1.0087x; 1.0004x over previous
.LBB0_880:
	s_or_b32 s22, s36, 0x180
	s_cmp_ge_i32 s46, s22
	v_cmp_eq_u32_e64 s[0:1], 0, v211
	v_lshrrev_b32_e32 v151, 8, v243
	v_lshlrev_b32_e32 v151, 4, v151
	v_and_or_b32 v151, v243, 15, v151
	v_lshlrev_b32_e32 v147, 2, v211
	s_cbranch_scc1 .LBB0_919
	s_add_u32 s4, s76, 0xb200000
	s_addc_u32 s5, s77, 0
	s_add_u32 s23, s76, 0xc600000
	s_addc_u32 s24, s77, 0
	s_add_u32 s25, s76, 0xcb00000
	s_addc_u32 s26, s77, 0
	v_bfe_u32 v1, v243, 4, 4
	s_add_u32 s27, s76, 0x110000
	v_lshl_add_u32 v2, v1, 4, 0
	s_movk_i32 s2, 0x470
	v_and_b32_e32 v146, 31, v243
	s_addc_u32 s28, s77, 0
	v_lshlrev_b32_e32 v150, 8, v151
	v_mad_u32_u24 v153, v1, s2, v2
	s_movk_i32 s2, 0x110
	v_lshlrev_b32_e32 v160, 1, v151
	v_lshrrev_b32_e32 v8, 3, v160
	v_lshrrev_b32_e32 v9, 4, v160
	v_xor_b32_e32 v8, v8, v9
	v_and_b32_e32 v8, 1, v8
	v_mul_u32_u24_e32 v8, 24, v8
	v_xor_b32_e32 v160, v160, v8
	s_add_u32 s29, s76, 0x150000
	v_mov_b32_e32 v149, 0
	v_lshlrev_b32_e32 v152, 3, v1
	v_add_u32_e32 v0, 0x2000, v150
	v_mad_u32_u24 v1, v146, s2, 0
	v_add_u32_e32 v3, 0, v210
	v_mul_u32_u24_e32 v4, 0x110, v151
	v_add_u32_e32 v5, 64, v160
	v_mul_u32_u24_e32 v6, 0x90, v146
	v_mad_i32_i24 v7, v211, -4, v146
	v_mbcnt_lo_u32_b32 v183, -1, 0
	s_addc_u32 s30, s77, 0
	s_mov_b32 s7, 0
	v_cndmask_b32_e64 v145, 0, 1.0, s[0:1]
	v_or_b32_e32 v161, 1, v147
	v_or_b32_e32 v162, 2, v147
	v_or_b32_e32 v163, 3, v147
	v_or_b32_e32 v164, 8, v147
	v_or_b32_e32 v165, 9, v147
	v_or_b32_e32 v166, 10, v147
	v_or_b32_e32 v167, 11, v147
	v_or_b32_e32 v168, 16, v147
	v_or_b32_e32 v169, 17, v147
	v_or_b32_e32 v170, 18, v147
	v_or_b32_e32 v171, 19, v147
	v_or_b32_e32 v172, 24, v147
	v_or_b32_e32 v173, 25, v147
	v_or_b32_e32 v174, 26, v147
	v_or_b32_e32 v175, 27, v147
	v_cmp_eq_u32_e64 s[2:3], 0, v243
	v_sub_u32_e32 v176, 0, v7
	v_subrev_u32_e32 v177, 27, v7
	v_lshlrev_b32_e32 v154, 1, v144
	v_mov_b32_e32 v155, v149
	v_mov_b32_e32 v178, 0x80
	v_lshlrev_b32_e32 v156, 1, v0
	v_add_u32_e32 v179, v2, v4
	v_add_u32_e32 v180, v153, v5
	v_add_u32_e32 v181, v1, v210
	s_movk_i32 s31, 0x81
	v_add_u32_e32 v182, v3, v6
	s_mov_b64 s[12:13], 0x14800800
	s_mov_b32 s33, 0x14800000
	s_add_i32 s35, 0, 0x24010
	v_mbcnt_hi_u32_b32 v184, -1, v183
	v_mov_b32_e32 v185, 0xf149f2ca
	s_branch .LBB0_884

.LBB0_912:
	v_sub_f32_e32 v64, v64, v159
	v_exp_f32_e32 v195, v64
	v_sub_f32_e32 v64, v81, v159
	v_exp_f32_e32 v196, v64
	v_sub_f32_e32 v64, v65, v159
	v_exp_f32_e32 v197, v64
	v_sub_f32_e32 v64, v82, v159
	v_exp_f32_e32 v198, v64
	v_sub_f32_e32 v64, v66, v159
	v_exp_f32_e32 v199, v64
	v_sub_f32_e32 v64, v83, v159
	v_exp_f32_e32 v200, v64
	v_sub_f32_e32 v64, v67, v159
	v_exp_f32_e32 v201, v64
	v_sub_f32_e32 v64, v84, v159
	v_exp_f32_e32 v84, v64
	v_sub_f32_e32 v64, v68, v159
	v_exp_f32_e32 v202, v64
	v_sub_f32_e32 v64, v85, v159
	v_exp_f32_e32 v85, v64
	v_sub_f32_e32 v64, v69, v159
	v_exp_f32_e32 v203, v64
	v_sub_f32_e32 v64, v86, v159
	v_exp_f32_e32 v86, v64
	v_sub_f32_e32 v64, v70, v159
	v_exp_f32_e32 v204, v64
	v_sub_f32_e32 v64, v87, v159
	v_exp_f32_e32 v87, v64
	v_sub_f32_e32 v64, v71, v159
	v_exp_f32_e32 v205, v64
	v_sub_f32_e32 v64, v88, v159
	v_exp_f32_e32 v88, v64
	v_sub_f32_e32 v64, v72, v159
	v_exp_f32_e32 v206, v64
	v_sub_f32_e32 v64, v89, v159
	v_exp_f32_e32 v89, v64
	v_sub_f32_e32 v64, v73, v159
	v_exp_f32_e32 v207, v64
	v_sub_f32_e32 v64, v90, v159
	v_exp_f32_e32 v90, v64
	v_sub_f32_e32 v64, v74, v159
	v_exp_f32_e32 v208, v64
	v_sub_f32_e32 v64, v91, v159
	v_exp_f32_e32 v91, v64
	v_sub_f32_e32 v64, v75, v159
	v_sub_f32_e32 v80, v80, v159
	v_exp_f32_e32 v209, v64
	v_sub_f32_e32 v64, v92, v159
	v_exp_f32_e32 v194, v80
	v_exp_f32_e32 v92, v64
	v_sub_f32_e32 v64, v76, v159
	v_exp_f32_e32 v212, v64
	v_sub_f32_e32 v64, v93, v159
	v_exp_f32_e32 v93, v64
	v_sub_f32_e32 v64, v77, v159
	v_exp_f32_e32 v213, v64
	v_sub_f32_e32 v64, v94, v159
	v_add_u32_e32 v214, 0x4000, v182
	v_exp_f32_e32 v94, v64
	v_cvt_pk_bf16_f32 v64, v194, v196
	v_cvt_pk_bf16_f32 v65, v198, v200
	v_cvt_pk_bf16_f32 v66, v84, v85
	v_cvt_pk_bf16_f32 v67, v86, v87
	ds_read_b128 v[68:71], v214 offset:1024
	v_sub_f32_e32 v72, v95, v159
	v_exp_f32_e32 v95, v72
	s_waitcnt lgkmcnt(0)
	v_mfma_f32_32x32x16_bf16 v[32:47], v[64:67], v[68:71], v[32:47]
	v_cvt_pk_bf16_f32 v72, v88, v89
	v_cvt_pk_bf16_f32 v73, v90, v91
	v_cvt_pk_bf16_f32 v74, v92, v93
	v_cvt_pk_bf16_f32 v75, v94, v95
	ds_read_b128 v[68:71], v214 offset:1056
	v_cvt_pk_bf16_f32 v80, v195, v197
	v_cvt_pk_bf16_f32 v81, v199, v201
	s_waitcnt lgkmcnt(0)
	v_mfma_f32_32x32x16_bf16 v[32:47], v[72:75], v[68:71], v[32:47]
	v_cvt_pk_bf16_f32 v82, v202, v203
	v_cvt_pk_bf16_f32 v83, v204, v205
	ds_read_b128 v[68:71], v214 offset:1088
	v_sub_f32_e32 v76, v78, v159
	v_exp_f32_e32 v215, v76
	v_sub_f32_e32 v76, v79, v159
	v_exp_f32_e32 v216, v76
	s_waitcnt lgkmcnt(0)
	v_mfma_f32_32x32x16_bf16 v[32:47], v[80:83], v[68:71], v[32:47]
	v_cvt_pk_bf16_f32 v76, v206, v207
	v_cvt_pk_bf16_f32 v77, v208, v209
	v_cvt_pk_bf16_f32 v78, v212, v213
	v_cvt_pk_bf16_f32 v79, v215, v216
	ds_read_b128 v[68:71], v214 offset:1120
	v_add_u32_e32 v214, 0x5000, v182
	v_add_f32_e32 v194, v194, v195
	s_waitcnt lgkmcnt(0)
	v_mfma_f32_32x32x16_bf16 v[32:47], v[76:79], v[68:71], v[32:47]
	ds_read_b128 v[68:71], v214 offset:1536
	v_add_f32_e32 v194, 0, v194
	v_add_f32_e32 v195, v196, v197
	v_add_f32_e32 v194, v195, v194
	v_add_f32_e32 v195, v200, v201
	v_add_f32_e32 v84, v84, v202
	v_add_f32_e32 v85, v85, v203
	s_waitcnt lgkmcnt(0)
	v_mfma_f32_32x32x16_bf16 v[48:63], v[64:67], v[68:71], v[48:63]
	ds_read_b128 v[68:71], v214 offset:1568
	s_add_i32 s43, s43, 64
	s_cmp_eq_u32 s41, s47
	v_subrev_u32_e32 v191, 64, v191
	s_waitcnt lgkmcnt(0)
	v_mfma_f32_32x32x16_bf16 v[48:63], v[72:75], v[68:71], v[48:63]
	ds_read_b128 v[68:71], v214 offset:1600
	s_waitcnt lgkmcnt(0)
	v_mfma_f32_32x32x16_bf16 v[48:63], v[80:83], v[68:71], v[48:63]
	ds_read_b128 v[68:71], v214 offset:1632
	v_add_u32_e32 v214, 0x6800, v182
	s_waitcnt lgkmcnt(0)
	v_mfma_f32_32x32x16_bf16 v[48:63], v[76:79], v[68:71], v[48:63]
	ds_read_b128 v[68:71], v214
	s_waitcnt lgkmcnt(0)
	v_mfma_f32_32x32x16_bf16 v[16:31], v[64:67], v[68:71], v[16:31]
	ds_read_b128 v[68:71], v214 offset:32
	s_waitcnt lgkmcnt(0)
	v_mfma_f32_32x32x16_bf16 v[16:31], v[72:75], v[68:71], v[16:31]
	ds_read_b128 v[68:71], v214 offset:64
	s_waitcnt lgkmcnt(0)
	v_mfma_f32_32x32x16_bf16 v[16:31], v[80:83], v[68:71], v[16:31]
	v_add_f32_e32 v68, v198, v199
	v_add_f32_e32 v194, v68, v194
	ds_read_b128 v[68:71], v214 offset:96
	v_add_f32_e32 v194, v195, v194
	v_add_f32_e32 v84, v84, v194
	v_add_u32_e32 v194, 0x7800, v182
	v_add_f32_e32 v84, v85, v84
	s_waitcnt lgkmcnt(0)
	v_mfma_f32_32x32x16_bf16 v[16:31], v[76:79], v[68:71], v[16:31]
	ds_read_b128 v[68:71], v194 offset:512
	v_add_f32_e32 v85, v86, v204
	v_add_f32_e32 v84, v85, v84
	v_add_f32_e32 v85, v87, v205
	s_waitcnt lgkmcnt(0)
	v_mfma_f32_32x32x16_bf16 v[0:15], v[64:67], v[68:71], v[0:15]
	ds_read_b128 v[64:67], v194 offset:544
	v_add_f32_e32 v68, v85, v84
	v_add_f32_e32 v69, v88, v206
	v_add_f32_e32 v68, v69, v68
	v_add_f32_e32 v69, v89, v207
	v_add_f32_e32 v68, v69, v68
	v_add_f32_e32 v69, v90, v208
	s_waitcnt lgkmcnt(0)
	v_mfma_f32_32x32x16_bf16 v[0:15], v[72:75], v[64:67], v[0:15]
	ds_read_b128 v[64:67], v194 offset:576
	v_add_f32_e32 v68, v69, v68
	v_add_f32_e32 v69, v91, v209
	v_add_f32_e32 v68, v69, v68
	v_add_f32_e32 v69, v92, v212
	v_add_f32_e32 v68, v69, v68
	v_add_f32_e32 v69, v93, v213
	s_waitcnt lgkmcnt(0)
	v_mfma_f32_32x32x16_bf16 v[0:15], v[80:83], v[64:67], v[0:15]
	v_add_f32_e32 v64, v69, v68
	ds_read_b128 v[66:69], v194 offset:608
	v_add_f32_e32 v65, v94, v215
	v_add_f32_e32 v64, v65, v64
	v_add_f32_e32 v65, v95, v216
	v_add_f32_e32 v64, v65, v64
	v_fmac_f32_e32 v64, v192, v193
	s_waitcnt lgkmcnt(0)
	v_mfma_f32_32x32x16_bf16 v[0:15], v[76:79], v[66:69], v[0:15]
	s_cbranch_scc1 .LBB0_914
	v_mov_b32_e32 v192, v64
	v_mov_b32_e32 v193, v159
	s_mov_b32 s48, s47
	s_branch .LBB0_897

.LBB0_919:
	s_or_b32 s23, s36, 0x280
	s_cmp_ge_i32 s46, s23
	s_cbranch_scc1 .LBB0_958
	s_add_u32 s4, s76, 0xb200000
	s_addc_u32 s5, s77, 0
	s_add_u32 s24, s76, 0xc600000
	s_addc_u32 s25, s77, 0
	s_add_u32 s26, s76, 0xcb00000
	s_addc_u32 s27, s77, 0
	v_bfe_u32 v1, v243, 4, 4
	s_add_u32 s28, s76, 0x110000
	v_lshl_add_u32 v2, v1, 4, 0
	s_movk_i32 s2, 0x470
	v_and_b32_e32 v146, 31, v243
	s_addc_u32 s29, s77, 0
	v_lshlrev_b32_e32 v148, 8, v151
	v_mad_u32_u24 v158, v1, s2, v2
	s_movk_i32 s2, 0x110
	v_mul_u32_u24_e32 v4, 0x110, v151
	v_lshlrev_b32_e32 v151, 1, v151
	v_lshrrev_b32_e32 v8, 3, v151
	v_lshrrev_b32_e32 v9, 4, v151
	v_xor_b32_e32 v8, v8, v9
	v_and_b32_e32 v8, 1, v8
	v_mul_u32_u24_e32 v8, 24, v8
	v_xor_b32_e32 v151, v151, v8
	s_add_u32 s30, s76, 0x150000
	v_mov_b32_e32 v145, 0
	v_cmp_eq_u32_e64 s[0:1], 0, v211
	v_lshlrev_b32_e32 v150, 3, v1
	v_add_u32_e32 v0, 0x2000, v148
	v_mad_u32_u24 v1, v146, s2, 0
	v_add_u32_e32 v3, 0, v210
	v_add_u32_e32 v5, 64, v151
	v_mul_u32_u24_e32 v6, 0x90, v146
	v_mad_i32_i24 v7, v211, -4, v146
	v_mbcnt_lo_u32_b32 v181, -1, 0
	s_addc_u32 s31, s77, 0
	s_mov_b32 s7, 0
	v_cndmask_b32_e64 v149, 0, 1.0, s[0:1]
	v_or_b32_e32 v159, 1, v147
	v_or_b32_e32 v160, 2, v147
	v_or_b32_e32 v161, 3, v147
	v_or_b32_e32 v162, 8, v147
	v_or_b32_e32 v163, 9, v147
	v_or_b32_e32 v164, 10, v147
	v_or_b32_e32 v165, 11, v147
	v_or_b32_e32 v166, 16, v147
	v_or_b32_e32 v167, 17, v147
	v_or_b32_e32 v168, 18, v147
	v_or_b32_e32 v169, 19, v147
	v_or_b32_e32 v170, 24, v147
	v_or_b32_e32 v171, 25, v147
	v_or_b32_e32 v172, 26, v147
	v_or_b32_e32 v173, 27, v147
	v_cmp_eq_u32_e64 s[2:3], 0, v243
	v_sub_u32_e32 v174, 0, v7
	v_subrev_u32_e32 v175, 27, v7
	v_lshlrev_b32_e32 v152, 1, v144
	v_mov_b32_e32 v153, v145
	v_mov_b32_e32 v176, 0x80
	v_lshlrev_b32_e32 v154, 1, v0
	v_add_u32_e32 v177, v2, v4
	v_add_u32_e32 v178, v158, v5
	v_add_u32_e32 v179, v1, v210
	s_movk_i32 s33, 0x81
	v_add_u32_e32 v180, v3, v6
	s_mov_b64 s[12:13], 0x14800800
	s_mov_b32 s34, 0x14800000
	s_add_i32 s35, 0, 0x24010
	v_mbcnt_hi_u32_b32 v182, -1, v181
	v_mov_b32_e32 v183, 0xf149f2ca
	s_branch .LBB0_923

.LBB0_951:
	v_sub_f32_e32 v64, v64, v157
	v_exp_f32_e32 v193, v64
	v_sub_f32_e32 v64, v81, v157
	v_exp_f32_e32 v194, v64
	v_sub_f32_e32 v64, v65, v157
	v_exp_f32_e32 v195, v64
	v_sub_f32_e32 v64, v82, v157
	v_exp_f32_e32 v196, v64
	v_sub_f32_e32 v64, v66, v157
	v_exp_f32_e32 v197, v64
	v_sub_f32_e32 v64, v83, v157
	v_exp_f32_e32 v198, v64
	v_sub_f32_e32 v64, v67, v157
	v_exp_f32_e32 v199, v64
	v_sub_f32_e32 v64, v84, v157
	v_exp_f32_e32 v84, v64
	v_sub_f32_e32 v64, v68, v157
	v_exp_f32_e32 v200, v64
	v_sub_f32_e32 v64, v85, v157
	v_exp_f32_e32 v85, v64
	v_sub_f32_e32 v64, v69, v157
	v_exp_f32_e32 v201, v64
	v_sub_f32_e32 v64, v86, v157
	v_exp_f32_e32 v86, v64
	v_sub_f32_e32 v64, v70, v157
	v_exp_f32_e32 v202, v64
	v_sub_f32_e32 v64, v87, v157
	v_exp_f32_e32 v87, v64
	v_sub_f32_e32 v64, v71, v157
	v_exp_f32_e32 v203, v64
	v_sub_f32_e32 v64, v88, v157
	v_exp_f32_e32 v88, v64
	v_sub_f32_e32 v64, v72, v157
	v_exp_f32_e32 v204, v64
	v_sub_f32_e32 v64, v89, v157
	v_exp_f32_e32 v89, v64
	v_sub_f32_e32 v64, v73, v157
	v_exp_f32_e32 v205, v64
	v_sub_f32_e32 v64, v90, v157
	v_exp_f32_e32 v90, v64
	v_sub_f32_e32 v64, v74, v157
	v_exp_f32_e32 v206, v64
	v_sub_f32_e32 v64, v91, v157
	v_exp_f32_e32 v91, v64
	v_sub_f32_e32 v64, v75, v157
	v_sub_f32_e32 v80, v80, v157
	v_exp_f32_e32 v207, v64
	v_sub_f32_e32 v64, v92, v157
	v_exp_f32_e32 v192, v80
	v_exp_f32_e32 v92, v64
	v_sub_f32_e32 v64, v76, v157
	v_exp_f32_e32 v208, v64
	v_sub_f32_e32 v64, v93, v157
	v_exp_f32_e32 v93, v64
	v_sub_f32_e32 v64, v77, v157
	v_exp_f32_e32 v209, v64
	v_sub_f32_e32 v64, v94, v157
	v_add_u32_e32 v211, 0x4000, v180
	v_exp_f32_e32 v94, v64
	v_cvt_pk_bf16_f32 v64, v192, v194
	v_cvt_pk_bf16_f32 v65, v196, v198
	v_cvt_pk_bf16_f32 v66, v84, v85
	v_cvt_pk_bf16_f32 v67, v86, v87
	ds_read_b128 v[68:71], v211 offset:1024
	v_sub_f32_e32 v72, v95, v157
	v_exp_f32_e32 v95, v72
	s_waitcnt lgkmcnt(0)
	v_mfma_f32_32x32x16_bf16 v[32:47], v[64:67], v[68:71], v[32:47]
	v_cvt_pk_bf16_f32 v72, v88, v89
	v_cvt_pk_bf16_f32 v73, v90, v91
	v_cvt_pk_bf16_f32 v74, v92, v93
	v_cvt_pk_bf16_f32 v75, v94, v95
	ds_read_b128 v[68:71], v211 offset:1056
	v_cvt_pk_bf16_f32 v80, v193, v195
	v_cvt_pk_bf16_f32 v81, v197, v199
	s_waitcnt lgkmcnt(0)
	v_mfma_f32_32x32x16_bf16 v[32:47], v[72:75], v[68:71], v[32:47]
	v_cvt_pk_bf16_f32 v82, v200, v201
	v_cvt_pk_bf16_f32 v83, v202, v203
	ds_read_b128 v[68:71], v211 offset:1088
	v_sub_f32_e32 v76, v78, v157
	v_exp_f32_e32 v212, v76
	v_sub_f32_e32 v76, v79, v157
	v_exp_f32_e32 v213, v76
	s_waitcnt lgkmcnt(0)
	v_mfma_f32_32x32x16_bf16 v[32:47], v[80:83], v[68:71], v[32:47]
	v_cvt_pk_bf16_f32 v76, v204, v205
	v_cvt_pk_bf16_f32 v77, v206, v207
	v_cvt_pk_bf16_f32 v78, v208, v209
	v_cvt_pk_bf16_f32 v79, v212, v213
	ds_read_b128 v[68:71], v211 offset:1120
	v_add_u32_e32 v211, 0x5000, v180
	v_add_f32_e32 v192, v192, v193
	s_waitcnt lgkmcnt(0)
	v_mfma_f32_32x32x16_bf16 v[32:47], v[76:79], v[68:71], v[32:47]
	ds_read_b128 v[68:71], v211 offset:1536
	v_add_f32_e32 v192, 0, v192
	v_add_f32_e32 v193, v194, v195
	v_add_f32_e32 v192, v193, v192
	v_add_f32_e32 v193, v198, v199
	v_add_f32_e32 v84, v84, v200
	v_add_f32_e32 v85, v85, v201
	s_waitcnt lgkmcnt(0)
	v_mfma_f32_32x32x16_bf16 v[48:63], v[64:67], v[68:71], v[48:63]
	ds_read_b128 v[68:71], v211 offset:1568
	s_add_i32 s43, s43, 64
	s_cmp_eq_u32 s41, s47
	v_subrev_u32_e32 v189, 64, v189
	s_waitcnt lgkmcnt(0)
	v_mfma_f32_32x32x16_bf16 v[48:63], v[72:75], v[68:71], v[48:63]
	ds_read_b128 v[68:71], v211 offset:1600
	s_waitcnt lgkmcnt(0)
	v_mfma_f32_32x32x16_bf16 v[48:63], v[80:83], v[68:71], v[48:63]
	ds_read_b128 v[68:71], v211 offset:1632
	v_add_u32_e32 v211, 0x6800, v180
	s_waitcnt lgkmcnt(0)
	v_mfma_f32_32x32x16_bf16 v[48:63], v[76:79], v[68:71], v[48:63]
	ds_read_b128 v[68:71], v211
	s_waitcnt lgkmcnt(0)
	v_mfma_f32_32x32x16_bf16 v[16:31], v[64:67], v[68:71], v[16:31]
	ds_read_b128 v[68:71], v211 offset:32
	s_waitcnt lgkmcnt(0)
	v_mfma_f32_32x32x16_bf16 v[16:31], v[72:75], v[68:71], v[16:31]
	ds_read_b128 v[68:71], v211 offset:64
	s_waitcnt lgkmcnt(0)
	v_mfma_f32_32x32x16_bf16 v[16:31], v[80:83], v[68:71], v[16:31]
	v_add_f32_e32 v68, v196, v197
	v_add_f32_e32 v192, v68, v192
	ds_read_b128 v[68:71], v211 offset:96
	v_add_f32_e32 v192, v193, v192
	v_add_f32_e32 v84, v84, v192
	v_add_u32_e32 v192, 0x7800, v180
	v_add_f32_e32 v84, v85, v84
	s_waitcnt lgkmcnt(0)
	v_mfma_f32_32x32x16_bf16 v[16:31], v[76:79], v[68:71], v[16:31]
	ds_read_b128 v[68:71], v192 offset:512
	v_add_f32_e32 v85, v86, v202
	v_add_f32_e32 v84, v85, v84
	v_add_f32_e32 v85, v87, v203
	s_waitcnt lgkmcnt(0)
	v_mfma_f32_32x32x16_bf16 v[0:15], v[64:67], v[68:71], v[0:15]
	ds_read_b128 v[64:67], v192 offset:544
	v_add_f32_e32 v68, v85, v84
	v_add_f32_e32 v69, v88, v204
	v_add_f32_e32 v68, v69, v68
	v_add_f32_e32 v69, v89, v205
	v_add_f32_e32 v68, v69, v68
	v_add_f32_e32 v69, v90, v206
	s_waitcnt lgkmcnt(0)
	v_mfma_f32_32x32x16_bf16 v[0:15], v[72:75], v[64:67], v[0:15]
	ds_read_b128 v[64:67], v192 offset:576
	v_add_f32_e32 v68, v69, v68
	v_add_f32_e32 v69, v91, v207
	v_add_f32_e32 v68, v69, v68
	v_add_f32_e32 v69, v92, v208
	v_add_f32_e32 v68, v69, v68
	v_add_f32_e32 v69, v93, v209
	s_waitcnt lgkmcnt(0)
	v_mfma_f32_32x32x16_bf16 v[0:15], v[80:83], v[64:67], v[0:15]
	v_add_f32_e32 v64, v69, v68
	ds_read_b128 v[66:69], v192 offset:608
	v_add_f32_e32 v65, v94, v212
	v_add_f32_e32 v64, v65, v64
	v_add_f32_e32 v65, v95, v213
	v_add_f32_e32 v64, v65, v64
	v_fmac_f32_e32 v64, v190, v191
	s_waitcnt lgkmcnt(0)
	v_mfma_f32_32x32x16_bf16 v[0:15], v[76:79], v[66:69], v[0:15]
	s_cbranch_scc1 .LBB0_953
	v_mov_b32_e32 v190, v64
	v_mov_b32_e32 v191, v157
	s_mov_b32 s48, s47
	s_branch .LBB0_936
